# v9 (pipelined MLA step, mid-step DMA issue) + residual-epilogue load pipelining in EpiResidNorm x2 and EpiResid, slot loads as dwordx4
# speedup vs baseline: 1.0143x; 1.0060x over previous
.LBB0_1000:
	s_lshl_b32 s0, s4, 5
	s_lshl_b32 s5, s53, 8
	s_lshl_b32 s1, s8, 8
	s_add_i32 s2, s5, s36
	s_or_b32 s0, s1, s0
	s_cmp_gt_i32 s53, 15
	v_lshl_or_b32 v162, v152, 3, s0
	s_cselect_b32 s0, 0x3000, 0
	s_lshl_b32 s12, s0, 2
	v_readlane_b32 s0, v255, 2
	v_readlane_b32 s1, v255, 3
	s_add_u32 s0, s0, s12
	v_ashrrev_i32_e32 v163, 31, v162
	s_addc_u32 s1, s1, 0
	v_lshlrev_b64 v[146:147], 2, v[162:163]
	v_lshl_add_u64 v[130:131], s[0:1], 0, v[146:147]
	s_movk_i32 s0, 0x4000
	v_or_b32_e32 v148, s2, v148
	v_lshl_add_u64 v[134:135], v[130:131], 0, s[26:27]
	v_add_co_u32_e32 v130, vcc, s0, v130
	v_ashrrev_i32_e32 v149, 31, v148
	v_readlane_b32 s0, v254, 61
	v_lshlrev_b64 v[150:151], 13, v[148:149]
	v_readlane_b32 s1, v254, 62
	v_addc_co_u32_e32 v131, vcc, 0, v131, vcc
	s_nop 0
	v_lshl_add_u64 v[150:151], s[0:1], 0, v[150:151]
	v_lshl_add_u64 v[150:151], v[150:151], 0, v[146:147]
	s_waitcnt vmcnt(0)
	s_barrier
	global_load_dwordx4 v[142:145], v[130:131], off
	global_load_dwordx4 v[138:141], v[134:135], off offset:16
	s_nop 0
	global_load_dwordx4 v[130:133], v[134:135], off offset:528
	s_nop 0
	global_load_dwordx4 v[134:137], v[134:135], off offset:512
	s_nop 0
	s_nop 0
	global_load_dwordx4 v[178:181], v[150:151], off offset:16
	global_load_dwordx4 v[182:185], v[150:151], off
	global_load_dwordx4 v[186:189], v[150:151], off offset:528
	global_load_dwordx4 v[190:193], v[150:151], off offset:512
	v_add_co_u32_e32 v164, vcc, 0x20000, v150
	s_nop 1
	v_addc_co_u32_e32 v165, vcc, 0, v151, vcc
	global_load_dwordx4 v[198:201], v[164:165], off offset:16
	global_load_dwordx4 v[202:205], v[164:165], off
	global_load_dwordx4 v[206:209], v[164:165], off offset:528
	global_load_dwordx4 v[214:217], v[164:165], off offset:512
	v_add_co_u32_e32 v164, vcc, 0x40000, v150
	s_nop 1
	v_addc_co_u32_e32 v165, vcc, 0, v151, vcc
	global_load_dwordx4 v[218:221], v[164:165], off offset:16
	global_load_dwordx4 v[222:225], v[164:165], off
	global_load_dwordx4 v[226:229], v[164:165], off offset:528
	global_load_dwordx4 v[230:233], v[164:165], off offset:512
	v_add_co_u32_e32 v164, vcc, 0x60000, v150
	s_nop 1
	v_addc_co_u32_e32 v165, vcc, 0, v151, vcc
	global_load_dwordx4 v[234:237], v[164:165], off offset:16
	global_load_dwordx4 v[238:241], v[164:165], off
	global_load_dwordx4 v[242:245], v[164:165], off offset:528
	global_load_dwordx4 v[154:157], v[164:165], off offset:512
	s_waitcnt vmcnt(15)
	v_pk_fma_f32 v[108:109], v[108:109], v[140:141], v[180:181]
	v_pk_fma_f32 v[106:107], v[106:107], v[138:139], v[178:179]
	v_add_co_u32_e32 v164, vcc, 0x100000, v150
	s_nop 1
	v_addc_co_u32_e32 v165, vcc, 0, v151, vcc
	global_load_dwordx4 v[178:181], v[164:165], off
	s_waitcnt vmcnt(15)
	v_pk_fma_f32 v[112:113], v[112:113], v[144:145], v[184:185]
	v_pk_fma_f32 v[110:111], v[110:111], v[142:143], v[182:183]
	global_load_dwordx4 v[182:185], v[164:165], off offset:16
	s_waitcnt vmcnt(15)
	v_pk_fma_f32 v[0:1], v[0:1], v[130:131], v[186:187]
	v_pk_fma_f32 v[2:3], v[2:3], v[132:133], v[188:189]
	global_load_dwordx4 v[186:189], v[164:165], off offset:528
	s_waitcnt vmcnt(15)
	v_pk_fma_f32 v[6:7], v[6:7], v[136:137], v[192:193]
	v_pk_fma_f32 v[4:5], v[4:5], v[134:135], v[190:191]
	global_load_dwordx4 v[190:193], v[164:165], off offset:512
	s_waitcnt vmcnt(15)
	v_pk_fma_f32 v[116:117], v[116:117], v[140:141], v[200:201]
	v_pk_fma_f32 v[114:115], v[114:115], v[138:139], v[198:199]
	v_add_co_u32_e32 v164, vcc, 0x120000, v150
	s_nop 1
	v_addc_co_u32_e32 v165, vcc, 0, v151, vcc
	global_load_dwordx4 v[198:201], v[164:165], off
	s_waitcnt vmcnt(15)
	v_pk_fma_f32 v[120:121], v[120:121], v[144:145], v[204:205]
	v_pk_fma_f32 v[118:119], v[118:119], v[142:143], v[202:203]
	global_load_dwordx4 v[202:205], v[164:165], off offset:16
	s_waitcnt vmcnt(15)
	v_pk_fma_f32 v[8:9], v[8:9], v[130:131], v[206:207]
	v_pk_fma_f32 v[10:11], v[10:11], v[132:133], v[208:209]
	global_load_dwordx4 v[206:209], v[164:165], off offset:528
	s_waitcnt vmcnt(15)
	v_pk_fma_f32 v[14:15], v[14:15], v[136:137], v[216:217]
	v_pk_fma_f32 v[12:13], v[12:13], v[134:135], v[214:215]
	global_load_dwordx4 v[214:217], v[164:165], off offset:512
	s_waitcnt vmcnt(15)
	v_pk_fma_f32 v[124:125], v[124:125], v[140:141], v[220:221]
	v_pk_fma_f32 v[122:123], v[122:123], v[138:139], v[218:219]
	v_add_co_u32_e32 v164, vcc, 0x140000, v150
	s_nop 1
	v_addc_co_u32_e32 v165, vcc, 0, v151, vcc
	global_load_dwordx4 v[218:221], v[164:165], off
	s_waitcnt vmcnt(15)
	v_pk_fma_f32 v[128:129], v[128:129], v[144:145], v[224:225]
	v_pk_fma_f32 v[126:127], v[126:127], v[142:143], v[222:223]
	global_load_dwordx4 v[222:225], v[164:165], off offset:16
	s_waitcnt vmcnt(15)
	v_pk_fma_f32 v[20:21], v[20:21], v[130:131], v[226:227]
	v_pk_fma_f32 v[22:23], v[22:23], v[132:133], v[228:229]
	global_load_dwordx4 v[226:229], v[164:165], off offset:528
	s_waitcnt vmcnt(15)
	v_pk_fma_f32 v[26:27], v[26:27], v[136:137], v[232:233]
	v_pk_fma_f32 v[24:25], v[24:25], v[134:135], v[230:231]
	global_load_dwordx4 v[230:233], v[164:165], off offset:512
	s_waitcnt vmcnt(15)
	v_pk_fma_f32 v[90:91], v[90:91], v[140:141], v[236:237]
	v_pk_fma_f32 v[88:89], v[88:89], v[138:139], v[234:235]
	v_add_co_u32_e32 v164, vcc, 0x160000, v150
	s_nop 1
	v_addc_co_u32_e32 v165, vcc, 0, v151, vcc
	global_load_dwordx4 v[234:237], v[164:165], off
	s_waitcnt vmcnt(15)
	v_pk_fma_f32 v[94:95], v[94:95], v[144:145], v[240:241]
	v_pk_fma_f32 v[92:93], v[92:93], v[142:143], v[238:239]
	global_load_dwordx4 v[238:241], v[164:165], off offset:16
	s_waitcnt vmcnt(15)
	v_pk_fma_f32 v[34:35], v[34:35], v[132:133], v[244:245]
	v_pk_fma_f32 v[32:33], v[32:33], v[130:131], v[242:243]
	global_load_dwordx4 v[242:245], v[164:165], off offset:528
	s_waitcnt vmcnt(15)
	v_pk_fma_f32 v[42:43], v[42:43], v[136:137], v[156:157]
	v_pk_fma_f32 v[40:41], v[40:41], v[134:135], v[154:155]
	global_load_dwordx4 v[154:157], v[164:165], off offset:512
	s_waitcnt vmcnt(15)
	v_pk_fma_f32 v[104:105], v[104:105], v[144:145], v[180:181]
	v_pk_fma_f32 v[102:103], v[102:103], v[142:143], v[178:179]
	s_waitcnt vmcnt(14)
	v_pk_fma_f32 v[100:101], v[100:101], v[140:141], v[184:185]
	v_pk_fma_f32 v[98:99], v[98:99], v[138:139], v[182:183]
	s_waitcnt vmcnt(13)
	v_pk_fma_f32 v[56:57], v[56:57], v[130:131], v[186:187]
	v_pk_fma_f32 v[58:59], v[58:59], v[132:133], v[188:189]
	s_waitcnt vmcnt(12)
	v_pk_fma_f32 v[62:63], v[62:63], v[136:137], v[192:193]
	v_pk_fma_f32 v[60:61], v[60:61], v[134:135], v[190:191]
	s_waitcnt vmcnt(11)
	v_pk_fma_f32 v[86:87], v[86:87], v[144:145], v[200:201]
	v_pk_fma_f32 v[84:85], v[84:85], v[142:143], v[198:199]
	s_waitcnt vmcnt(10)
	v_pk_fma_f32 v[82:83], v[82:83], v[140:141], v[204:205]
	v_pk_fma_f32 v[80:81], v[80:81], v[138:139], v[202:203]
	s_waitcnt vmcnt(9)
	v_pk_fma_f32 v[72:73], v[72:73], v[130:131], v[206:207]
	v_pk_fma_f32 v[74:75], v[74:75], v[132:133], v[208:209]
	s_waitcnt vmcnt(8)
	v_pk_fma_f32 v[78:79], v[78:79], v[136:137], v[216:217]
	v_pk_fma_f32 v[76:77], v[76:77], v[134:135], v[214:215]
	s_waitcnt vmcnt(7)
	v_pk_fma_f32 v[70:71], v[70:71], v[144:145], v[220:221]
	v_pk_fma_f32 v[68:69], v[68:69], v[142:143], v[218:219]
	s_waitcnt vmcnt(6)
	v_pk_fma_f32 v[66:67], v[66:67], v[140:141], v[224:225]
	v_pk_fma_f32 v[64:65], v[64:65], v[138:139], v[222:223]
	s_waitcnt vmcnt(5)
	v_pk_fma_f32 v[50:51], v[50:51], v[132:133], v[228:229]
	v_pk_fma_f32 v[48:49], v[48:49], v[130:131], v[226:227]
	s_waitcnt vmcnt(4)
	v_pk_fma_f32 v[54:55], v[54:55], v[136:137], v[232:233]
	v_pk_fma_f32 v[52:53], v[52:53], v[134:135], v[230:231]
	s_waitcnt vmcnt(3)
	v_pk_fma_f32 v[46:47], v[46:47], v[144:145], v[236:237]
	v_pk_fma_f32 v[44:45], v[44:45], v[142:143], v[234:235]
	s_waitcnt vmcnt(2)
	v_pk_fma_f32 v[38:39], v[38:39], v[140:141], v[240:241]
	v_pk_fma_f32 v[36:37], v[36:37], v[138:139], v[238:239]
	s_waitcnt vmcnt(1)
	v_pk_fma_f32 v[18:19], v[18:19], v[132:133], v[244:245]
	v_pk_fma_f32 v[16:17], v[16:17], v[130:131], v[242:243]
	s_waitcnt vmcnt(0)
	v_pk_fma_f32 v[28:29], v[28:29], v[134:135], v[154:155]
	v_pk_fma_f32 v[30:31], v[30:31], v[136:137], v[156:157]
	s_mov_b64 s[0:1], 0x160000
	s_lshl_b32 s0, s4, 2
	s_add_i32 s0, s0, 0
	v_cmp_eq_u32_e32 vcc, 0, v152
	v_mul_f32_e32 v132, v111, v111
	v_mul_f32_e32 v133, v113, v113
	v_fmac_f32_e32 v132, v110, v110
	v_fmac_f32_e32 v133, v112, v112
	v_add_f32_e32 v132, v132, v133
	v_mul_f32_e32 v133, v107, v107
	v_mul_f32_e32 v134, v109, v109
	v_fmac_f32_e32 v133, v106, v106
	v_fmac_f32_e32 v134, v108, v108
	v_add_f32_e32 v133, v133, v134
	v_add_f32_e32 v132, v132, v133
	v_mul_f32_e32 v133, v5, v5
	v_mul_f32_e32 v134, v7, v7
	v_fmac_f32_e32 v133, v4, v4
	v_fmac_f32_e32 v134, v6, v6
	v_add_f32_e32 v133, v133, v134
	v_add_f32_e32 v132, v133, v132
	v_mul_f32_e32 v133, v1, v1
	v_mul_f32_e32 v134, v3, v3
	v_fmac_f32_e32 v133, v0, v0
	v_fmac_f32_e32 v134, v2, v2
	v_mbcnt_lo_u32_b32 v96, -1, 0
	v_mbcnt_hi_u32_b32 v96, -1, v96
	v_add_f32_e32 v133, v133, v134
	v_lshlrev_b32_e32 v130, 2, v96
	v_xor_b32_e32 v131, 64, v130
	v_add_f32_e32 v132, v133, v132
	ds_bpermute_b32 v133, v131, v132
	v_xor_b32_e32 v130, 0x80, v130
	s_waitcnt lgkmcnt(0)
	v_add_f32_e32 v133, v132, v133
	ds_bpermute_b32 v134, v130, v133
	v_lshl_add_u32 v132, v172, 4, s0
	s_and_saveexec_b64 s[0:1], vcc
	s_cbranch_execz .LBB0_1002
	s_waitcnt lgkmcnt(0)
	v_add_f32_e32 v133, v133, v134
	ds_write_b32 v132, v133

.LBB0_1364:
	s_lshl_b32 s0, s4, 5
	s_lshl_b32 s5, s51, 8
	s_lshl_b32 s1, s8, 8
	s_add_i32 s2, s5, s36
	s_or_b32 s0, s1, s0
	s_cmp_gt_i32 s51, 15
	v_lshl_or_b32 v162, v152, 3, s0
	s_cselect_b32 s0, 0x3000, 0
	v_or_b32_e32 v148, s2, v148
	s_lshl_b32 s12, s0, 2
	v_ashrrev_i32_e32 v149, 31, v148
	s_add_u32 s0, s49, s12
	v_ashrrev_i32_e32 v163, 31, v162
	v_lshlrev_b64 v[150:151], 13, v[148:149]
	s_addc_u32 s1, s50, 0
	v_lshlrev_b64 v[146:147], 2, v[162:163]
	v_lshl_add_u64 v[150:151], s[96:97], 0, v[150:151]
	v_lshl_add_u64 v[134:135], s[0:1], 0, v[146:147]
	v_lshl_add_u64 v[150:151], v[150:151], 0, v[146:147]
	s_waitcnt vmcnt(0)
	s_barrier
	global_load_dwordx4 v[138:141], v[134:135], off offset:16
	global_load_dwordx4 v[142:145], v[134:135], off
	global_load_dwordx4 v[130:133], v[134:135], off offset:528
	s_nop 0
	global_load_dwordx4 v[134:137], v[134:135], off offset:512
	s_nop 0
	s_branch .Lmy_pad2
	s_nop 0
	s_nop 0
	s_nop 0
	s_nop 0
	s_nop 0
	s_nop 0
	s_nop 0
	s_nop 0
	s_nop 0
	s_nop 0
	s_nop 0
	s_nop 0
.Lmy_pad2:
	global_load_dwordx4 v[178:181], v[150:151], off offset:16
	global_load_dwordx4 v[182:185], v[150:151], off
	global_load_dwordx4 v[186:189], v[150:151], off offset:528
	global_load_dwordx4 v[190:193], v[150:151], off offset:512
	v_add_co_u32_e32 v164, vcc, 0x20000, v150
	s_nop 1
	v_addc_co_u32_e32 v165, vcc, 0, v151, vcc
	global_load_dwordx4 v[198:201], v[164:165], off offset:16
	global_load_dwordx4 v[202:205], v[164:165], off
	global_load_dwordx4 v[206:209], v[164:165], off offset:528
	global_load_dwordx4 v[214:217], v[164:165], off offset:512
	v_add_co_u32_e32 v164, vcc, 0x40000, v150
	s_nop 1
	v_addc_co_u32_e32 v165, vcc, 0, v151, vcc
	global_load_dwordx4 v[218:221], v[164:165], off offset:16
	global_load_dwordx4 v[222:225], v[164:165], off
	global_load_dwordx4 v[226:229], v[164:165], off offset:528
	global_load_dwordx4 v[230:233], v[164:165], off offset:512
	v_add_co_u32_e32 v164, vcc, 0x60000, v150
	s_nop 1
	v_addc_co_u32_e32 v165, vcc, 0, v151, vcc
	global_load_dwordx4 v[234:237], v[164:165], off offset:16
	global_load_dwordx4 v[238:241], v[164:165], off
	global_load_dwordx4 v[242:245], v[164:165], off offset:528
	global_load_dwordx4 v[154:157], v[164:165], off offset:512
	s_waitcnt vmcnt(15)
	v_pk_fma_f32 v[108:109], v[108:109], v[140:141], v[180:181]
	v_pk_fma_f32 v[106:107], v[106:107], v[138:139], v[178:179]
	v_add_co_u32_e32 v164, vcc, 0x100000, v150
	s_nop 1
	v_addc_co_u32_e32 v165, vcc, 0, v151, vcc
	global_load_dwordx4 v[178:181], v[164:165], off
	s_waitcnt vmcnt(15)
	v_pk_fma_f32 v[112:113], v[112:113], v[144:145], v[184:185]
	v_pk_fma_f32 v[110:111], v[110:111], v[142:143], v[182:183]
	global_load_dwordx4 v[182:185], v[164:165], off offset:16
	s_waitcnt vmcnt(15)
	v_pk_fma_f32 v[0:1], v[0:1], v[130:131], v[186:187]
	v_pk_fma_f32 v[2:3], v[2:3], v[132:133], v[188:189]
	global_load_dwordx4 v[186:189], v[164:165], off offset:528
	s_waitcnt vmcnt(15)
	v_pk_fma_f32 v[6:7], v[6:7], v[136:137], v[192:193]
	v_pk_fma_f32 v[4:5], v[4:5], v[134:135], v[190:191]
	global_load_dwordx4 v[190:193], v[164:165], off offset:512
	s_waitcnt vmcnt(15)
	v_pk_fma_f32 v[116:117], v[116:117], v[140:141], v[200:201]
	v_pk_fma_f32 v[114:115], v[114:115], v[138:139], v[198:199]
	v_add_co_u32_e32 v164, vcc, 0x120000, v150
	s_nop 1
	v_addc_co_u32_e32 v165, vcc, 0, v151, vcc
	global_load_dwordx4 v[198:201], v[164:165], off
	s_waitcnt vmcnt(15)
	v_pk_fma_f32 v[120:121], v[120:121], v[144:145], v[204:205]
	v_pk_fma_f32 v[118:119], v[118:119], v[142:143], v[202:203]
	global_load_dwordx4 v[202:205], v[164:165], off offset:16
	s_waitcnt vmcnt(15)
	v_pk_fma_f32 v[8:9], v[8:9], v[130:131], v[206:207]
	v_pk_fma_f32 v[10:11], v[10:11], v[132:133], v[208:209]
	global_load_dwordx4 v[206:209], v[164:165], off offset:528
	s_waitcnt vmcnt(15)
	v_pk_fma_f32 v[14:15], v[14:15], v[136:137], v[216:217]
	v_pk_fma_f32 v[12:13], v[12:13], v[134:135], v[214:215]
	global_load_dwordx4 v[214:217], v[164:165], off offset:512
	s_waitcnt vmcnt(15)
	v_pk_fma_f32 v[124:125], v[124:125], v[140:141], v[220:221]
	v_pk_fma_f32 v[122:123], v[122:123], v[138:139], v[218:219]
	v_add_co_u32_e32 v164, vcc, 0x140000, v150
	s_nop 1
	v_addc_co_u32_e32 v165, vcc, 0, v151, vcc
	global_load_dwordx4 v[218:221], v[164:165], off
	s_waitcnt vmcnt(15)
	v_pk_fma_f32 v[128:129], v[128:129], v[144:145], v[224:225]
	v_pk_fma_f32 v[126:127], v[126:127], v[142:143], v[222:223]
	global_load_dwordx4 v[222:225], v[164:165], off offset:16
	s_waitcnt vmcnt(15)
	v_pk_fma_f32 v[20:21], v[20:21], v[130:131], v[226:227]
	v_pk_fma_f32 v[22:23], v[22:23], v[132:133], v[228:229]
	global_load_dwordx4 v[226:229], v[164:165], off offset:528
	s_waitcnt vmcnt(15)
	v_pk_fma_f32 v[26:27], v[26:27], v[136:137], v[232:233]
	v_pk_fma_f32 v[24:25], v[24:25], v[134:135], v[230:231]
	global_load_dwordx4 v[230:233], v[164:165], off offset:512
	s_waitcnt vmcnt(15)
	v_pk_fma_f32 v[90:91], v[90:91], v[140:141], v[236:237]
	v_pk_fma_f32 v[88:89], v[88:89], v[138:139], v[234:235]
	v_add_co_u32_e32 v164, vcc, 0x160000, v150
	s_nop 1
	v_addc_co_u32_e32 v165, vcc, 0, v151, vcc
	global_load_dwordx4 v[234:237], v[164:165], off
	s_waitcnt vmcnt(15)
	v_pk_fma_f32 v[94:95], v[94:95], v[144:145], v[240:241]
	v_pk_fma_f32 v[92:93], v[92:93], v[142:143], v[238:239]
	global_load_dwordx4 v[238:241], v[164:165], off offset:16
	s_waitcnt vmcnt(15)
	v_pk_fma_f32 v[38:39], v[38:39], v[132:133], v[244:245]
	v_pk_fma_f32 v[36:37], v[36:37], v[130:131], v[242:243]
	global_load_dwordx4 v[242:245], v[164:165], off offset:528
	s_waitcnt vmcnt(15)
	v_pk_fma_f32 v[42:43], v[42:43], v[136:137], v[156:157]
	v_pk_fma_f32 v[40:41], v[40:41], v[134:135], v[154:155]
	global_load_dwordx4 v[154:157], v[164:165], off offset:512
	s_waitcnt vmcnt(15)
	v_pk_fma_f32 v[104:105], v[104:105], v[144:145], v[180:181]
	v_pk_fma_f32 v[102:103], v[102:103], v[142:143], v[178:179]
	s_waitcnt vmcnt(14)
	v_pk_fma_f32 v[100:101], v[100:101], v[140:141], v[184:185]
	v_pk_fma_f32 v[98:99], v[98:99], v[138:139], v[182:183]
	s_waitcnt vmcnt(13)
	v_pk_fma_f32 v[56:57], v[56:57], v[130:131], v[186:187]
	v_pk_fma_f32 v[58:59], v[58:59], v[132:133], v[188:189]
	s_waitcnt vmcnt(12)
	v_pk_fma_f32 v[62:63], v[62:63], v[136:137], v[192:193]
	v_pk_fma_f32 v[60:61], v[60:61], v[134:135], v[190:191]
	s_waitcnt vmcnt(11)
	v_pk_fma_f32 v[86:87], v[86:87], v[144:145], v[200:201]
	v_pk_fma_f32 v[84:85], v[84:85], v[142:143], v[198:199]
	s_waitcnt vmcnt(10)
	v_pk_fma_f32 v[82:83], v[82:83], v[140:141], v[204:205]
	v_pk_fma_f32 v[80:81], v[80:81], v[138:139], v[202:203]
	s_waitcnt vmcnt(9)
	v_pk_fma_f32 v[72:73], v[72:73], v[130:131], v[206:207]
	v_pk_fma_f32 v[74:75], v[74:75], v[132:133], v[208:209]
	s_waitcnt vmcnt(8)
	v_pk_fma_f32 v[78:79], v[78:79], v[136:137], v[216:217]
	v_pk_fma_f32 v[76:77], v[76:77], v[134:135], v[214:215]
	s_waitcnt vmcnt(7)
	v_pk_fma_f32 v[70:71], v[70:71], v[144:145], v[220:221]
	v_pk_fma_f32 v[68:69], v[68:69], v[142:143], v[218:219]
	s_waitcnt vmcnt(6)
	v_pk_fma_f32 v[66:67], v[66:67], v[140:141], v[224:225]
	v_pk_fma_f32 v[64:65], v[64:65], v[138:139], v[222:223]
	s_waitcnt vmcnt(5)
	v_pk_fma_f32 v[50:51], v[50:51], v[132:133], v[228:229]
	v_pk_fma_f32 v[48:49], v[48:49], v[130:131], v[226:227]
	s_waitcnt vmcnt(4)
	v_pk_fma_f32 v[54:55], v[54:55], v[136:137], v[232:233]
	v_pk_fma_f32 v[52:53], v[52:53], v[134:135], v[230:231]
	s_waitcnt vmcnt(3)
	v_pk_fma_f32 v[46:47], v[46:47], v[144:145], v[236:237]
	v_pk_fma_f32 v[44:45], v[44:45], v[142:143], v[234:235]
	s_waitcnt vmcnt(2)
	v_pk_fma_f32 v[34:35], v[34:35], v[140:141], v[240:241]
	v_pk_fma_f32 v[32:33], v[32:33], v[138:139], v[238:239]
	s_waitcnt vmcnt(1)
	v_pk_fma_f32 v[18:19], v[18:19], v[132:133], v[244:245]
	v_pk_fma_f32 v[16:17], v[16:17], v[130:131], v[242:243]
	s_waitcnt vmcnt(0)
	v_pk_fma_f32 v[28:29], v[28:29], v[134:135], v[154:155]
	v_pk_fma_f32 v[30:31], v[30:31], v[136:137], v[156:157]
	s_mov_b64 s[0:1], 0x160000
	s_lshl_b32 s0, s4, 2
	s_add_i32 s0, s0, 0
	v_cmp_eq_u32_e32 vcc, 0, v152
	v_mul_f32_e32 v132, v111, v111
	v_mul_f32_e32 v133, v113, v113
	v_fmac_f32_e32 v132, v110, v110
	v_fmac_f32_e32 v133, v112, v112
	v_add_f32_e32 v132, v132, v133
	v_mul_f32_e32 v133, v107, v107
	v_mul_f32_e32 v134, v109, v109
	v_fmac_f32_e32 v133, v106, v106
	v_fmac_f32_e32 v134, v108, v108
	v_add_f32_e32 v133, v133, v134
	v_add_f32_e32 v132, v132, v133
	v_mul_f32_e32 v133, v5, v5
	v_mul_f32_e32 v134, v7, v7
	v_fmac_f32_e32 v133, v4, v4
	v_fmac_f32_e32 v134, v6, v6
	v_add_f32_e32 v133, v133, v134
	v_add_f32_e32 v132, v133, v132
	v_mul_f32_e32 v133, v1, v1
	v_mul_f32_e32 v134, v3, v3
	v_fmac_f32_e32 v133, v0, v0
	v_fmac_f32_e32 v134, v2, v2
	v_mbcnt_lo_u32_b32 v96, -1, 0
	v_mbcnt_hi_u32_b32 v96, -1, v96
	v_add_f32_e32 v133, v133, v134
	v_lshlrev_b32_e32 v130, 2, v96
	v_xor_b32_e32 v131, 64, v130
	v_add_f32_e32 v132, v133, v132
	ds_bpermute_b32 v133, v131, v132
	v_xor_b32_e32 v130, 0x80, v130
	s_waitcnt lgkmcnt(0)
	v_add_f32_e32 v133, v132, v133
	ds_bpermute_b32 v134, v130, v133
	v_lshl_add_u32 v132, v172, 4, s0
	s_and_saveexec_b64 s[0:1], vcc
	s_cbranch_execz .LBB0_1366
	s_waitcnt lgkmcnt(0)
	v_add_f32_e32 v133, v133, v134
	ds_write_b32 v132, v133
